# P1: 13th (dt-only) column tile removed from the tile grid; dt computed inside the pn==0 tiles' K loop (2 extra MFMAs per block per wave, W_dt fragments double-buffered)
# speedup vs baseline: 1.0066x; 1.0066x over previous
.LBB0_386:
	s_nop 0
	v_readlane_b32 s0, v244, 47
	v_readlane_b32 s1, v244, 48
	s_cmp_lt_i32 s0, 2
	v_readlane_b32 s2, v244, 49
	v_readlane_b32 s3, v244, 50
	s_cselect_b64 s[0:1], -1, 0
	s_and_b64 s[2:3], s[0:1], s[18:19]
	s_andn2_b64 vcc, exec, s[2:3]
	s_cbranch_vccnz .LBB0_453
	v_readlane_b32 s4, v244, 51
	s_cmpk_lt_i32 s4, 0x900
	s_cselect_b64 s[0:1], -1, 0
	s_cmpk_gt_i32 s4, 0x8ff
	v_readfirstlane_b32 s8, v182
	s_cbranch_scc1 .LBB0_389
	v_readlane_b32 s6, v244, 51
	s_ashr_i32 s4, s6, 31
	s_lshr_b32 s4, s4, 29
	s_add_i32 s4, s6, s4
	s_ashr_i32 s5, s4, 3
	s_and_b32 s4, s4, -8
	s_sub_i32 s4, s6, s4
	s_cmp_lt_i32 s4, 0
	s_movk_i32 s6, 0x121
	s_cselect_b32 s6, s6, 0x120
	s_mul_i32 s4, s4, s6
	s_add_i32 s4, s4, s5
	s_mul_hi_i32 s5, s4, 0x55555556
	s_lshr_b32 s6, s5, 31
	s_ashr_i32 s5, s5, 5
	s_add_i32 s5, s5, s6
	s_lshl_b32 s6, s5, 3
	s_mulk_i32 s5, 0x60
	s_sub_i32 s4, s4, s5
	s_bfe_i32 s5, s4, 0x80000
	s_bfe_u32 s5, s5, 0x3000c
	s_add_i32 s5, s4, s5
	s_bfe_i32 s7, s5, 0x80000
	s_and_b32 s5, s5, 0xf8
	s_sub_i32 s4, s4, s5
	s_sext_i32_i16 s7, s7
	s_sext_i32_i8 s4, s4
	s_add_i32 s4, s6, s4
	s_ashr_i32 s6, s7, 3

.LBB0_392:
	v_readlane_b32 s12, v244, 0
	v_readlane_b32 s13, v244, 1
	v_readlane_b32 s18, v244, 6
	v_readlane_b32 s19, v244, 7
	s_add_u32 s43, s18, 0x6000000
	s_mov_b64 s[12:13], 0x80
	v_readlane_b32 s16, v244, 4
	s_addc_u32 s44, s19, 0
	s_and_b32 s1, s1, 3
	s_add_i32 m0, s7, 0x18000
	v_lshl_add_u64 v[6:7], v[6:7], 0, s[12:13]
	v_readlane_b32 s14, v244, 2
	s_lshl_b32 s5, s0, 13
	s_lshl_b32 s16, s1, 12
	s_waitcnt vmcnt(2)
	s_barrier
	global_load_lds_dwordx4 v[6:7], off
	v_lshl_add_u64 v[4:5], v[4:5], 0, s[12:13]
	s_add_i32 m0, s7, 0x1a000
	s_add_i32 s45, s7, 0x8000
	s_add_i32 s46, s7, 0xa000
	v_readlane_b32 s15, v244, 3
	global_load_lds_dwordx4 v[4:5], off
	v_lshl_add_u64 v[0:1], v[0:1], 0, s[12:13]
	s_mov_b32 m0, s45
	s_add_u32 s14, s34, 0x40080
	global_load_lds_dwordx4 v[0:1], off
	v_lshl_add_u64 v[0:1], v[2:3], 0, s[12:13]
	s_mov_b32 m0, s46
	s_addc_u32 s15, s35, 0
	global_load_lds_dwordx4 v[0:1], off
	s_add_i32 m0, s7, 0x1c000
	v_lshl_add_u64 v[0:1], s[14:15], 0, v[130:131]
	global_load_lds_dwordx4 v[0:1], off
	v_lshl_add_u64 v[0:1], s[14:15], 0, v[134:135]
	s_add_i32 m0, s7, 0x1e000
	v_lshlrev_b32_e32 v4, 2, v182
	global_load_lds_dwordx4 v[0:1], off
	v_lshrrev_b32_e32 v0, 4, v182
	v_and_b32_e32 v0, 3, v0
	v_and_b32_e32 v1, 15, v182
	v_lshlrev_b32_e32 v3, 4, v0
	v_lshl_or_b32 v139, s0, 6, v1
	v_lshl_or_b32 v1, v1, 6, v3
	v_and_b32_e32 v4, 32, v4
	s_cmpk_lt_u32 s8, 0x100
	v_lshlrev_b32_e32 v2, 3, v0
	v_bitop3_b32 v5, v1, s5, v4 bitop3:0xde
	v_lshlrev_b32_e32 v1, 6, v182
	s_movk_i32 s0, 0x3c0
	s_cselect_b64 s[14:15], -1, 0
	s_cmp_eq_u32 s1, 0
	v_readlane_b32 s17, v244, 5
	v_and_or_b32 v1, v1, s0, v3
	v_lshl_or_b32 v138, s1, 5, v2
	s_cselect_b64 s[0:1], -1, 0
	v_cmp_gt_u32_e32 vcc, 2, v0
	v_bitop3_b32 v145, s16, v1, v4 bitop3:0xf6
	s_and_b64 s[16:17], s[0:1], vcc
	v_readlane_b32 s0, v244, 51
	v_lshlrev_b32_e32 v136, 5, v0
	s_ashr_i32 s48, s0, 31
	v_lshl_add_u64 v[0:1], s[18:19], 0, v[136:137]
	s_mov_b64 s[0:1], 0x1a000000
	v_lshl_add_u64 v[140:141], v[0:1], 0, s[0:1]
	v_lshlrev_b32_e32 v0, 8, v182
	v_and_b32_e32 v0, 0x38000, v0
	v_lshlrev_b32_e32 v1, 11, v10
	v_or3_b32 v0, v8, v0, v1
	v_add_u32_e32 v142, v0, v9
	v_lshlrev_b32_e32 v0, 4, v11
	s_waitcnt vmcnt(6)
	v_and_b32_e32 v0, 0x78000, v0
	v_or3_b32 v0, v8, v0, v1
	s_add_i32 s50, 0, 0x10000
	s_add_i32 s51, 0, 0x14000
	s_ashr_i32 s47, s86, 31
	v_mov_b32_e32 v143, v137
	v_add_u32_e32 v146, v0, v9
	v_mov_b32_e32 v147, v137
	v_mov_b64_e32 v[148:149], 0x900
	v_mov_b64_e32 v[150:151], 0x8ff
	s_movk_i32 s49, 0x121
	v_add_u32_e32 v154, s50, v145
	v_add_u32_e32 v155, s51, v145
	v_add_u32_e32 v156, 0, v5
	s_mov_b32 s52, 0
	s_barrier
	s_branch .LBB0_395

.LBB0_395:
	s_add_i32 s52, s52, 1
	s_mul_i32 s0, s52, s47
	s_mul_hi_u32 s1, s52, s86
	s_add_i32 s1, s1, s0
	s_mul_i32 s0, s52, s86
	v_readlane_b32 s5, v244, 51
	s_add_u32 s26, s0, s5
	s_addc_u32 s27, s1, s48
	v_cmp_gt_i64_e32 vcc, s[26:27], v[150:151]
	v_cmp_lt_i64_e64 s[0:1], s[26:27], v[148:149]
	s_cbranch_vccnz .LBB0_397
	s_ashr_i32 s5, s26, 31
	s_lshr_b32 s5, s5, 29
	s_add_i32 s5, s26, s5
	s_ashr_i32 s8, s5, 3
	s_and_b32 s5, s5, -8
	s_sub_i32 s5, s26, s5
	s_cmp_lt_i32 s5, 0
	s_cselect_b32 s18, s49, 0x120
	s_mul_i32 s5, s5, s18
	s_add_i32 s5, s5, s8
	s_mul_hi_i32 s8, s5, 0x55555556
	s_lshr_b32 s18, s8, 31
	s_ashr_i32 s8, s8, 5
	s_add_i32 s8, s8, s18
	s_lshl_b32 s19, s8, 3
	s_sub_i32 s18, 0xc0, s19
	s_min_i32 s24, s18, 8
	s_abs_i32 s18, s24
	v_cvt_f32_u32_e32 v0, s18
	s_sub_i32 s26, 0, s18
	s_mulk_i32 s8, 0x60
	s_sub_i32 s5, s5, s8
	v_rcp_iflag_f32_e32 v0, v0
	s_abs_i32 s8, s5
	s_xor_b32 s25, s5, s24
	s_ashr_i32 s25, s25, 31
	v_mul_f32_e32 v0, 0x4f7ffffe, v0
	v_cvt_u32_f32_e32 v0, v0
	s_nop 0
	v_readfirstlane_b32 s27, v0
	s_mul_i32 s26, s26, s27
	s_mul_hi_u32 s26, s27, s26
	s_add_i32 s27, s27, s26
	s_mul_hi_u32 s26, s8, s27
	s_mul_i32 s27, s26, s18
	s_sub_i32 s8, s8, s27
	s_add_i32 s28, s26, 1
	s_sub_i32 s27, s8, s18
	s_cmp_ge_u32 s8, s18
	s_cselect_b32 s26, s28, s26
	s_cselect_b32 s8, s27, s8
	s_add_i32 s27, s26, 1
	s_cmp_ge_u32 s8, s18
	s_cselect_b32 s8, s27, s26
	s_xor_b32 s8, s8, s25
	s_sub_i32 s18, s8, s25
	s_mul_i32 s8, s18, s24
	s_sub_i32 s5, s5, s8
	s_add_i32 s24, s19, s5
.LBB0_397:
	v_readlane_b32 s56, v244, 0
	v_readlane_b32 s57, v244, 1
	v_readlane_b32 s58, v244, 2
	v_readlane_b32 s59, v244, 3
	v_readlane_b32 s60, v244, 4
	v_readlane_b32 s61, v244, 5
	s_ashr_i32 s25, s24, 31
	v_readlane_b32 s62, v244, 6
	v_readlane_b32 s63, v244, 7
	s_mov_b64 s[56:57], s[60:61]
	s_lshl_b64 s[26:27], s[24:25], 19
	s_mov_b64 s[58:59], s[62:63]
	s_add_u32 s26, s58, s26
	s_addc_u32 s27, s59, s27
	s_and_b64 s[28:29], s[0:1], exec
	s_cselect_b32 s5, s27, s31
	s_cselect_b32 s8, s26, s30
	s_ashr_i32 s19, s18, 31
	s_lshl_b64 s[28:29], s[18:19], 19
	s_add_u32 s28, s33, s28
	s_addc_u32 s29, s38, s29
	s_and_b64 s[36:37], s[0:1], exec
	s_cselect_b32 s19, s29, s35
	s_cselect_b32 s25, s28, s34
	s_add_u32 s30, s30, 0x40080
	s_addc_u32 s31, s31, 0
	s_add_u32 s53, s34, 0x100
	v_mov_b32_e32 v0, 0
	s_addc_u32 s54, s35, 0
	s_mov_b32 s55, -2
	v_mov_b32_e32 v1, v0
	v_mov_b32_e32 v2, v0
	v_mov_b32_e32 v3, v0
	v_mov_b32_e32 v4, v0
	v_mov_b32_e32 v5, v0
	v_mov_b32_e32 v6, v0
	v_mov_b32_e32 v7, v0
	v_mov_b32_e32 v16, v0
	v_mov_b32_e32 v17, v0
	v_mov_b32_e32 v18, v0
	v_mov_b32_e32 v19, v0
	v_mov_b32_e32 v20, v0
	v_mov_b32_e32 v21, v0
	v_mov_b32_e32 v22, v0
	v_mov_b32_e32 v23, v0
	v_mov_b32_e32 v32, v0
	v_mov_b32_e32 v33, v0
	v_mov_b32_e32 v34, v0
	v_mov_b32_e32 v35, v0
	v_mov_b32_e32 v36, v0
	v_mov_b32_e32 v37, v0
	v_mov_b32_e32 v38, v0
	v_mov_b32_e32 v39, v0
	v_mov_b32_e32 v48, v0
	v_mov_b32_e32 v49, v0
	v_mov_b32_e32 v50, v0
	v_mov_b32_e32 v51, v0
	v_mov_b32_e32 v52, v0
	v_mov_b32_e32 v53, v0
	v_mov_b32_e32 v54, v0
	v_mov_b32_e32 v55, v0
	v_mov_b32_e32 v8, v0
	v_mov_b32_e32 v9, v0
	v_mov_b32_e32 v10, v0
	v_mov_b32_e32 v11, v0
	v_mov_b32_e32 v12, v0
	v_mov_b32_e32 v13, v0
	v_mov_b32_e32 v14, v0
	v_mov_b32_e32 v15, v0
	v_mov_b32_e32 v24, v0
	v_mov_b32_e32 v25, v0
	v_mov_b32_e32 v26, v0
	v_mov_b32_e32 v27, v0
	v_mov_b32_e32 v28, v0
	v_mov_b32_e32 v29, v0
	v_mov_b32_e32 v30, v0
	v_mov_b32_e32 v31, v0
	v_mov_b32_e32 v40, v0
	v_mov_b32_e32 v41, v0
	v_mov_b32_e32 v42, v0
	v_mov_b32_e32 v43, v0
	v_mov_b32_e32 v44, v0
	v_mov_b32_e32 v45, v0
	v_mov_b32_e32 v46, v0
	v_mov_b32_e32 v47, v0
	v_mov_b32_e32 v56, v0
	v_mov_b32_e32 v57, v0
	v_mov_b32_e32 v58, v0
	v_mov_b32_e32 v59, v0
	v_mov_b32_e32 v60, v0
	v_mov_b32_e32 v61, v0
	v_mov_b32_e32 v62, v0
	v_mov_b32_e32 v63, v0
	v_mov_b32_e32 v64, v0
	v_mov_b32_e32 v65, v0
	v_mov_b32_e32 v66, v0
	v_mov_b32_e32 v67, v0
	v_mov_b32_e32 v68, v0
	v_mov_b32_e32 v69, v0
	v_mov_b32_e32 v70, v0
	v_mov_b32_e32 v71, v0
	v_mov_b32_e32 v80, v0
	v_mov_b32_e32 v81, v0
	v_mov_b32_e32 v82, v0
	v_mov_b32_e32 v83, v0
	v_mov_b32_e32 v84, v0
	v_mov_b32_e32 v85, v0
	v_mov_b32_e32 v86, v0
	v_mov_b32_e32 v87, v0
	v_mov_b32_e32 v96, v0
	v_mov_b32_e32 v97, v0
	v_mov_b32_e32 v98, v0
	v_mov_b32_e32 v99, v0
	v_mov_b32_e32 v100, v0
	v_mov_b32_e32 v101, v0
	v_mov_b32_e32 v102, v0
	v_mov_b32_e32 v103, v0
	v_mov_b32_e32 v112, v0
	v_mov_b32_e32 v113, v0
	v_mov_b32_e32 v114, v0
	v_mov_b32_e32 v115, v0
	v_mov_b32_e32 v116, v0
	v_mov_b32_e32 v117, v0
	v_mov_b32_e32 v118, v0
	v_mov_b32_e32 v119, v0
	v_mov_b32_e32 v72, v0
	v_mov_b32_e32 v73, v0
	v_mov_b32_e32 v74, v0
	v_mov_b32_e32 v75, v0
	v_mov_b32_e32 v76, v0
	v_mov_b32_e32 v77, v0
	v_mov_b32_e32 v78, v0
	v_mov_b32_e32 v79, v0
	v_mov_b32_e32 v88, v0
	v_mov_b32_e32 v89, v0
	v_mov_b32_e32 v90, v0
	v_mov_b32_e32 v91, v0
	v_mov_b32_e32 v92, v0
	v_mov_b32_e32 v93, v0
	v_mov_b32_e32 v94, v0
	v_mov_b32_e32 v95, v0
	v_mov_b32_e32 v104, v0
	v_mov_b32_e32 v105, v0
	v_mov_b32_e32 v106, v0
	v_mov_b32_e32 v107, v0
	v_mov_b32_e32 v108, v0
	v_mov_b32_e32 v109, v0
	v_mov_b32_e32 v110, v0
	v_mov_b32_e32 v111, v0
	v_mov_b32_e32 v120, v0
	v_mov_b32_e32 v121, v0
	v_mov_b32_e32 v122, v0
	v_mov_b32_e32 v123, v0
	v_mov_b32_e32 v124, v0
	v_mov_b32_e32 v125, v0
	v_mov_b32_e32 v126, v0
	v_mov_b32_e32 v127, v0
	s_cmp_eq_u32 s6, 0
	s_cselect_b32 s84, 1, 0
	s_cbranch_scc0 .Ldtf_nosetup
	v_readfirstlane_b32 s85, v182
	s_bfe_u32 s85, s85, 0x20006
	v_readlane_b32 s98, v244, 6
	v_readlane_b32 s99, v244, 7
	s_add_u32 s100, s98, 0x1a000000
	s_addc_u32 s101, s99, 0
	s_add_u32 s98, s98, 0x18600000
	s_addc_u32 s99, s99, 0
	v_and_b32_e32 v245, 15, v182
	v_bfe_u32 v254, v182, 4, 2
	v_lshlrev_b32_e32 v245, 11, v245
	v_lshl_add_u32 v245, v254, 4, v245
	v_mov_b32_e32 v246, 0
	v_mov_b32_e32 v247, 0
	v_mov_b32_e32 v248, 0
	v_mov_b32_e32 v249, 0
	v_mov_b32_e32 v250, 0
	v_mov_b32_e32 v251, 0
	v_mov_b32_e32 v252, 0
	v_mov_b32_e32 v253, 0
	global_load_dwordx4 v[232:235], v245, s[98:99]
	global_load_dwordx4 v[236:239], v245, s[98:99] offset:64
	s_add_u32 s98, s98, 0x80
	s_addc_u32 s99, s99, 0
	s_waitcnt vmcnt(0)
	s_branch .Ldtf_loop
.Ldtf_nosetup:
.LBB0_398:
	ds_read_b128 v[158:161], v154
	ds_read_b128 v[162:165], v154 offset:1024
	ds_read_b128 v[166:169], v154 offset:2048
	ds_read_b128 v[170:173], v154 offset:3072
	ds_read_b128 v[174:177], v155
	ds_read_b128 v[178:181], v155 offset:1024
	ds_read_b128 v[184:187], v155 offset:2048
	ds_read_b128 v[188:191], v155 offset:3072
	s_add_u32 s34, s30, 0xfffc0080
	s_addc_u32 s35, s31, -1
	s_cmp_eq_u32 s55, 12
	s_cselect_b32 s37, s5, s35
	s_cselect_b32 s36, s8, s34
	s_cselect_b32 s35, s19, s54
	s_cselect_b32 s34, s25, s53
	v_lshl_add_u64 v[152:153], s[30:31], 0, v[142:143]
	s_add_i32 m0, s7, 0xc000
	ds_read_b128 v[192:195], v156
	ds_read_b128 v[196:199], v156 offset:1024
	ds_read_b128 v[200:203], v156 offset:2048
	ds_read_b128 v[204:207], v156 offset:3072
	ds_read_b128 v[208:211], v156 offset:4096
	ds_read_b128 v[212:215], v156 offset:5120
	ds_read_b128 v[216:219], v156 offset:6144
	ds_read_b128 v[220:223], v156 offset:7168
	global_load_lds_dwordx4 v[152:153], off
	v_lshl_add_u64 v[152:153], s[30:31], 0, v[146:147]
	s_add_i32 m0, s7, 0xe000
	s_nop 0
	global_load_lds_dwordx4 v[152:153], off
	s_waitcnt vmcnt(8)
	s_waitcnt lgkmcnt(0)
	s_barrier
	s_setprio 1
	s_waitcnt lgkmcnt(0)
	v_mfma_f32_16x16x32_bf16 v[124:127], v[158:161], v[192:195], v[124:127]
	v_mfma_f32_16x16x32_bf16 v[120:123], v[166:169], v[192:195], v[120:123]
	v_mfma_f32_16x16x32_bf16 v[108:111], v[158:161], v[200:203], v[108:111]
	v_mfma_f32_16x16x32_bf16 v[104:107], v[166:169], v[200:203], v[104:107]
	v_mfma_f32_16x16x32_bf16 v[92:95], v[158:161], v[208:211], v[92:95]
	v_mfma_f32_16x16x32_bf16 v[88:91], v[166:169], v[208:211], v[88:91]
	v_mfma_f32_16x16x32_bf16 v[76:79], v[158:161], v[216:219], v[76:79]
	v_mfma_f32_16x16x32_bf16 v[72:75], v[166:169], v[216:219], v[72:75]
	v_mfma_f32_16x16x32_bf16 v[124:127], v[162:165], v[196:199], v[124:127]
	v_mfma_f32_16x16x32_bf16 v[120:123], v[170:173], v[196:199], v[120:123]
	v_mfma_f32_16x16x32_bf16 v[108:111], v[162:165], v[204:207], v[108:111]
	v_mfma_f32_16x16x32_bf16 v[104:107], v[170:173], v[204:207], v[104:107]
	v_mfma_f32_16x16x32_bf16 v[92:95], v[162:165], v[212:215], v[92:95]
	v_mfma_f32_16x16x32_bf16 v[88:91], v[170:173], v[212:215], v[88:91]
	v_mfma_f32_16x16x32_bf16 v[76:79], v[162:165], v[220:223], v[76:79]
	v_mfma_f32_16x16x32_bf16 v[72:75], v[170:173], v[220:223], v[72:75]
	s_setprio 0
	s_setprio 1
	v_mfma_f32_16x16x32_bf16 v[116:119], v[174:177], v[192:195], v[116:119]
	v_mfma_f32_16x16x32_bf16 v[112:115], v[184:187], v[192:195], v[112:115]
	v_mfma_f32_16x16x32_bf16 v[100:103], v[174:177], v[200:203], v[100:103]
	v_mfma_f32_16x16x32_bf16 v[96:99], v[184:187], v[200:203], v[96:99]
	v_mfma_f32_16x16x32_bf16 v[84:87], v[174:177], v[208:211], v[84:87]
	v_mfma_f32_16x16x32_bf16 v[80:83], v[184:187], v[208:211], v[80:83]
	v_mfma_f32_16x16x32_bf16 v[68:71], v[174:177], v[216:219], v[68:71]
	v_mfma_f32_16x16x32_bf16 v[64:67], v[184:187], v[216:219], v[64:67]
	v_mfma_f32_16x16x32_bf16 v[116:119], v[178:181], v[196:199], v[116:119]
	v_mfma_f32_16x16x32_bf16 v[112:115], v[188:191], v[196:199], v[112:115]
	v_mfma_f32_16x16x32_bf16 v[100:103], v[178:181], v[204:207], v[100:103]
	v_mfma_f32_16x16x32_bf16 v[96:99], v[188:191], v[204:207], v[96:99]
	v_mfma_f32_16x16x32_bf16 v[84:87], v[178:181], v[212:215], v[84:87]
	v_mfma_f32_16x16x32_bf16 v[80:83], v[188:191], v[212:215], v[80:83]
	v_mfma_f32_16x16x32_bf16 v[68:71], v[178:181], v[220:223], v[68:71]
	v_mfma_f32_16x16x32_bf16 v[64:67], v[188:191], v[220:223], v[64:67]
	s_setprio 0
	s_barrier
	s_add_i32 s56, s50, s39
	v_lshl_add_u64 v[152:153], s[34:35], 0, v[130:131]
	s_mov_b32 m0, s56
	ds_read_b128 v[192:195], v156 offset:16384
	ds_read_b128 v[196:199], v156 offset:17408
	ds_read_b128 v[200:203], v156 offset:18432
	ds_read_b128 v[204:207], v156 offset:19456
	ds_read_b128 v[208:211], v156 offset:20480
	ds_read_b128 v[212:215], v156 offset:21504
	ds_read_b128 v[216:219], v156 offset:22528
	ds_read_b128 v[220:223], v156 offset:23552
	global_load_lds_dwordx4 v[152:153], off
	s_add_i32 m0, s56, 0x2000
	s_add_u32 s56, s34, 0x40000
	v_lshl_add_u64 v[224:225], s[34:35], 0, v[134:135]
	s_addc_u32 s57, s35, 0
	s_add_i32 s58, s51, s39
	global_load_lds_dwordx4 v[224:225], off
	v_lshl_add_u64 v[226:227], s[56:57], 0, v[130:131]
	s_mov_b32 m0, s58
	v_lshl_add_u64 v[228:229], s[36:37], 0, v[132:133]
	global_load_lds_dwordx4 v[226:227], off
	v_lshl_add_u64 v[226:227], s[56:57], 0, v[134:135]
	s_add_i32 m0, s58, 0x2000
	s_nop 0
	global_load_lds_dwordx4 v[226:227], off
	v_lshl_add_u64 v[226:227], s[36:37], 0, v[128:129]
	s_mov_b32 m0, s7
	s_nop 0
	global_load_lds_dwordx4 v[226:227], off
	s_mov_b32 m0, s40
	s_nop 0
	global_load_lds_dwordx4 v[228:229], off
	s_waitcnt vmcnt(8)
	s_waitcnt lgkmcnt(0)
	s_barrier
	s_setprio 1
	s_waitcnt lgkmcnt(0)
	v_mfma_f32_16x16x32_bf16 v[60:63], v[158:161], v[192:195], v[60:63]
	v_mfma_f32_16x16x32_bf16 v[56:59], v[166:169], v[192:195], v[56:59]
	v_mfma_f32_16x16x32_bf16 v[44:47], v[158:161], v[200:203], v[44:47]
	v_mfma_f32_16x16x32_bf16 v[40:43], v[166:169], v[200:203], v[40:43]
	v_mfma_f32_16x16x32_bf16 v[28:31], v[158:161], v[208:211], v[28:31]
	v_mfma_f32_16x16x32_bf16 v[24:27], v[166:169], v[208:211], v[24:27]
	v_mfma_f32_16x16x32_bf16 v[12:15], v[158:161], v[216:219], v[12:15]
	v_mfma_f32_16x16x32_bf16 v[8:11], v[166:169], v[216:219], v[8:11]
	v_mfma_f32_16x16x32_bf16 v[60:63], v[162:165], v[196:199], v[60:63]
	v_mfma_f32_16x16x32_bf16 v[56:59], v[170:173], v[196:199], v[56:59]
	v_mfma_f32_16x16x32_bf16 v[44:47], v[162:165], v[204:207], v[44:47]
	v_mfma_f32_16x16x32_bf16 v[40:43], v[170:173], v[204:207], v[40:43]
	v_mfma_f32_16x16x32_bf16 v[28:31], v[162:165], v[212:215], v[28:31]
	v_mfma_f32_16x16x32_bf16 v[24:27], v[170:173], v[212:215], v[24:27]
	v_mfma_f32_16x16x32_bf16 v[12:15], v[162:165], v[220:223], v[12:15]
	v_mfma_f32_16x16x32_bf16 v[8:11], v[170:173], v[220:223], v[8:11]
	s_setprio 0
	s_setprio 1
	v_mfma_f32_16x16x32_bf16 v[52:55], v[174:177], v[192:195], v[52:55]
	v_mfma_f32_16x16x32_bf16 v[48:51], v[184:187], v[192:195], v[48:51]
	v_mfma_f32_16x16x32_bf16 v[36:39], v[174:177], v[200:203], v[36:39]
	v_mfma_f32_16x16x32_bf16 v[32:35], v[184:187], v[200:203], v[32:35]
	v_mfma_f32_16x16x32_bf16 v[20:23], v[174:177], v[208:211], v[20:23]
	v_mfma_f32_16x16x32_bf16 v[16:19], v[184:187], v[208:211], v[16:19]
	v_mfma_f32_16x16x32_bf16 v[4:7], v[174:177], v[216:219], v[4:7]
	v_mfma_f32_16x16x32_bf16 v[0:3], v[184:187], v[216:219], v[0:3]
	v_mfma_f32_16x16x32_bf16 v[52:55], v[178:181], v[196:199], v[52:55]
	v_mfma_f32_16x16x32_bf16 v[48:51], v[188:191], v[196:199], v[48:51]
	v_mfma_f32_16x16x32_bf16 v[36:39], v[178:181], v[204:207], v[36:39]
	v_mfma_f32_16x16x32_bf16 v[32:35], v[188:191], v[204:207], v[32:35]
	v_mfma_f32_16x16x32_bf16 v[20:23], v[178:181], v[212:215], v[20:23]
	v_mfma_f32_16x16x32_bf16 v[16:19], v[188:191], v[212:215], v[16:19]
	v_mfma_f32_16x16x32_bf16 v[4:7], v[178:181], v[220:223], v[4:7]
	v_mfma_f32_16x16x32_bf16 v[0:3], v[188:191], v[220:223], v[0:3]
	s_setprio 0
	s_barrier
	s_add_i32 s56, 0, 0x18000
	v_add_u32_e32 v136, s56, v145
	s_add_i32 s57, 0, 0x1c000
	ds_read_b128 v[158:161], v136
	ds_read_b128 v[162:165], v136 offset:1024
	ds_read_b128 v[166:169], v136 offset:2048
	ds_read_b128 v[170:173], v136 offset:3072
	v_add_u32_e32 v136, s57, v145
	ds_read_b128 v[174:177], v136
	ds_read_b128 v[178:181], v136 offset:1024
	ds_read_b128 v[184:187], v136 offset:2048
	ds_read_b128 v[188:191], v136 offset:3072
	s_add_u32 s36, s36, 0x40000
	s_addc_u32 s37, s37, 0
	s_mov_b32 m0, s41
	v_lshl_add_u64 v[230:231], s[36:37], 0, v[128:129]
	ds_read_b128 v[192:195], v156 offset:32768
	ds_read_b128 v[196:199], v156 offset:33792
	ds_read_b128 v[200:203], v156 offset:34816
	ds_read_b128 v[204:207], v156 offset:35840
	ds_read_b128 v[208:211], v156 offset:36864
	ds_read_b128 v[212:215], v156 offset:37888
	ds_read_b128 v[216:219], v156 offset:38912
	ds_read_b128 v[220:223], v156 offset:39936
	global_load_lds_dwordx4 v[230:231], off
	v_lshl_add_u64 v[230:231], s[36:37], 0, v[132:133]
	s_mov_b32 m0, s42
	s_nop 0
	global_load_lds_dwordx4 v[230:231], off
	s_waitcnt vmcnt(8)
	s_waitcnt lgkmcnt(0)
	s_barrier
	s_setprio 1
	s_waitcnt lgkmcnt(0)
	v_mfma_f32_16x16x32_bf16 v[124:127], v[158:161], v[192:195], v[124:127]
	v_mfma_f32_16x16x32_bf16 v[120:123], v[166:169], v[192:195], v[120:123]
	v_mfma_f32_16x16x32_bf16 v[108:111], v[158:161], v[200:203], v[108:111]
	v_mfma_f32_16x16x32_bf16 v[104:107], v[166:169], v[200:203], v[104:107]
	v_mfma_f32_16x16x32_bf16 v[92:95], v[158:161], v[208:211], v[92:95]
	v_mfma_f32_16x16x32_bf16 v[88:91], v[166:169], v[208:211], v[88:91]
	v_mfma_f32_16x16x32_bf16 v[76:79], v[158:161], v[216:219], v[76:79]
	v_mfma_f32_16x16x32_bf16 v[72:75], v[166:169], v[216:219], v[72:75]
	v_mfma_f32_16x16x32_bf16 v[124:127], v[162:165], v[196:199], v[124:127]
	v_mfma_f32_16x16x32_bf16 v[120:123], v[170:173], v[196:199], v[120:123]
	v_mfma_f32_16x16x32_bf16 v[108:111], v[162:165], v[204:207], v[108:111]
	v_mfma_f32_16x16x32_bf16 v[104:107], v[170:173], v[204:207], v[104:107]
	v_mfma_f32_16x16x32_bf16 v[92:95], v[162:165], v[212:215], v[92:95]
	v_mfma_f32_16x16x32_bf16 v[88:91], v[170:173], v[212:215], v[88:91]
	v_mfma_f32_16x16x32_bf16 v[76:79], v[162:165], v[220:223], v[76:79]
	v_mfma_f32_16x16x32_bf16 v[72:75], v[170:173], v[220:223], v[72:75]
	s_setprio 0
	s_setprio 1
	v_mfma_f32_16x16x32_bf16 v[116:119], v[174:177], v[192:195], v[116:119]
	v_mfma_f32_16x16x32_bf16 v[112:115], v[184:187], v[192:195], v[112:115]
	v_mfma_f32_16x16x32_bf16 v[100:103], v[174:177], v[200:203], v[100:103]
	v_mfma_f32_16x16x32_bf16 v[96:99], v[184:187], v[200:203], v[96:99]
	v_mfma_f32_16x16x32_bf16 v[84:87], v[174:177], v[208:211], v[84:87]
	v_mfma_f32_16x16x32_bf16 v[80:83], v[184:187], v[208:211], v[80:83]
	v_mfma_f32_16x16x32_bf16 v[68:71], v[174:177], v[216:219], v[68:71]
	v_mfma_f32_16x16x32_bf16 v[64:67], v[184:187], v[216:219], v[64:67]
	v_mfma_f32_16x16x32_bf16 v[116:119], v[178:181], v[196:199], v[116:119]
	v_mfma_f32_16x16x32_bf16 v[112:115], v[188:191], v[196:199], v[112:115]
	v_mfma_f32_16x16x32_bf16 v[100:103], v[178:181], v[204:207], v[100:103]
	v_mfma_f32_16x16x32_bf16 v[96:99], v[188:191], v[204:207], v[96:99]
	v_mfma_f32_16x16x32_bf16 v[84:87], v[178:181], v[212:215], v[84:87]
	v_mfma_f32_16x16x32_bf16 v[80:83], v[188:191], v[212:215], v[80:83]
	v_mfma_f32_16x16x32_bf16 v[68:71], v[178:181], v[220:223], v[68:71]
	v_mfma_f32_16x16x32_bf16 v[64:67], v[188:191], v[220:223], v[64:67]
	s_setprio 0
	s_barrier
	s_add_i32 s36, s56, s39
	v_lshl_add_u64 v[152:153], v[152:153], 0, s[12:13]
	s_mov_b32 m0, s36
	ds_read_b128 v[192:195], v156 offset:49152
	ds_read_b128 v[196:199], v156 offset:50176
	ds_read_b128 v[200:203], v156 offset:51200
	ds_read_b128 v[204:207], v156 offset:52224
	ds_read_b128 v[208:211], v156 offset:53248
	ds_read_b128 v[212:215], v156 offset:54272
	ds_read_b128 v[216:219], v156 offset:55296
	ds_read_b128 v[220:223], v156 offset:56320
	global_load_lds_dwordx4 v[152:153], off
	s_add_i32 m0, s36, 0x2000
	s_add_u32 s34, s34, 0x40080
	v_lshl_add_u64 v[152:153], v[224:225], 0, s[12:13]
	s_addc_u32 s35, s35, 0
	s_add_i32 s36, s57, s39
	global_load_lds_dwordx4 v[152:153], off
	v_lshl_add_u64 v[152:153], s[34:35], 0, v[130:131]
	s_mov_b32 m0, s36
	s_nop 0
	global_load_lds_dwordx4 v[152:153], off
	v_lshl_add_u64 v[152:153], s[34:35], 0, v[134:135]
	s_add_i32 m0, s36, 0x2000
	s_nop 0
	global_load_lds_dwordx4 v[152:153], off
	v_lshl_add_u64 v[152:153], v[226:227], 0, s[12:13]
	s_mov_b32 m0, s45
	s_nop 0
	global_load_lds_dwordx4 v[152:153], off
	v_lshl_add_u64 v[152:153], v[228:229], 0, s[12:13]
	s_mov_b32 m0, s46
	s_nop 0
	global_load_lds_dwordx4 v[152:153], off
	s_waitcnt vmcnt(8)
	s_waitcnt lgkmcnt(0)
	s_barrier
	s_setprio 1
	s_waitcnt lgkmcnt(0)
	v_mfma_f32_16x16x32_bf16 v[60:63], v[158:161], v[192:195], v[60:63]
	v_mfma_f32_16x16x32_bf16 v[56:59], v[166:169], v[192:195], v[56:59]
	v_mfma_f32_16x16x32_bf16 v[44:47], v[158:161], v[200:203], v[44:47]
	v_mfma_f32_16x16x32_bf16 v[40:43], v[166:169], v[200:203], v[40:43]
	v_mfma_f32_16x16x32_bf16 v[28:31], v[158:161], v[208:211], v[28:31]
	v_mfma_f32_16x16x32_bf16 v[24:27], v[166:169], v[208:211], v[24:27]
	v_mfma_f32_16x16x32_bf16 v[12:15], v[158:161], v[216:219], v[12:15]
	v_mfma_f32_16x16x32_bf16 v[8:11], v[166:169], v[216:219], v[8:11]
	v_mfma_f32_16x16x32_bf16 v[60:63], v[162:165], v[196:199], v[60:63]
	v_mfma_f32_16x16x32_bf16 v[56:59], v[170:173], v[196:199], v[56:59]
	v_mfma_f32_16x16x32_bf16 v[44:47], v[162:165], v[204:207], v[44:47]
	v_mfma_f32_16x16x32_bf16 v[40:43], v[170:173], v[204:207], v[40:43]
	v_mfma_f32_16x16x32_bf16 v[28:31], v[162:165], v[212:215], v[28:31]
	v_mfma_f32_16x16x32_bf16 v[24:27], v[170:173], v[212:215], v[24:27]
	v_mfma_f32_16x16x32_bf16 v[12:15], v[162:165], v[220:223], v[12:15]
	v_mfma_f32_16x16x32_bf16 v[8:11], v[170:173], v[220:223], v[8:11]
	s_setprio 0
	s_setprio 1
	v_mfma_f32_16x16x32_bf16 v[52:55], v[174:177], v[192:195], v[52:55]
	v_mfma_f32_16x16x32_bf16 v[48:51], v[184:187], v[192:195], v[48:51]
	v_mfma_f32_16x16x32_bf16 v[36:39], v[174:177], v[200:203], v[36:39]
	v_mfma_f32_16x16x32_bf16 v[32:35], v[184:187], v[200:203], v[32:35]
	v_mfma_f32_16x16x32_bf16 v[20:23], v[174:177], v[208:211], v[20:23]
	v_mfma_f32_16x16x32_bf16 v[16:19], v[184:187], v[208:211], v[16:19]
	v_mfma_f32_16x16x32_bf16 v[4:7], v[174:177], v[216:219], v[4:7]
	v_mfma_f32_16x16x32_bf16 v[0:3], v[184:187], v[216:219], v[0:3]
	v_mfma_f32_16x16x32_bf16 v[52:55], v[178:181], v[196:199], v[52:55]
	v_mfma_f32_16x16x32_bf16 v[48:51], v[188:191], v[196:199], v[48:51]
	v_mfma_f32_16x16x32_bf16 v[36:39], v[178:181], v[204:207], v[36:39]
	v_mfma_f32_16x16x32_bf16 v[32:35], v[188:191], v[204:207], v[32:35]
	v_mfma_f32_16x16x32_bf16 v[20:23], v[178:181], v[212:215], v[20:23]
	v_mfma_f32_16x16x32_bf16 v[16:19], v[188:191], v[212:215], v[16:19]
	v_mfma_f32_16x16x32_bf16 v[4:7], v[178:181], v[220:223], v[4:7]
	v_mfma_f32_16x16x32_bf16 v[0:3], v[188:191], v[220:223], v[0:3]
	s_setprio 0
	s_barrier
	s_add_i32 s55, s55, 2
	s_add_u32 s30, s30, 0x100
	s_addc_u32 s31, s31, 0
	s_add_u32 s53, s53, 0x100
	s_addc_u32 s54, s54, 0
	s_cmp_gt_u32 s55, 13
	s_cbranch_scc0 .LBB0_398
	s_branch .Ldtf_exit
.Ldtf_loop:
	ds_read_b128 v[158:161], v154
	ds_read_b128 v[162:165], v154 offset:1024
	ds_read_b128 v[166:169], v154 offset:2048
	ds_read_b128 v[170:173], v154 offset:3072
	ds_read_b128 v[174:177], v155
	ds_read_b128 v[178:181], v155 offset:1024
	ds_read_b128 v[184:187], v155 offset:2048
	ds_read_b128 v[188:191], v155 offset:3072
	s_add_u32 s34, s30, 0xfffc0080
	s_addc_u32 s35, s31, -1
	s_cmp_eq_u32 s55, 12
	s_cselect_b32 s37, s5, s35
	s_cselect_b32 s36, s8, s34
	s_cselect_b32 s35, s19, s54
	s_cselect_b32 s34, s25, s53
	v_lshl_add_u64 v[152:153], s[30:31], 0, v[142:143]
	s_add_i32 m0, s7, 0xc000
	ds_read_b128 v[192:195], v156
	ds_read_b128 v[196:199], v156 offset:1024
	ds_read_b128 v[200:203], v156 offset:2048
	ds_read_b128 v[204:207], v156 offset:3072
	ds_read_b128 v[208:211], v156 offset:4096
	ds_read_b128 v[212:215], v156 offset:5120
	ds_read_b128 v[216:219], v156 offset:6144
	ds_read_b128 v[220:223], v156 offset:7168
	global_load_lds_dwordx4 v[152:153], off
	v_lshl_add_u64 v[152:153], s[30:31], 0, v[146:147]
	s_add_i32 m0, s7, 0xe000
	s_nop 0
	global_load_lds_dwordx4 v[152:153], off
	global_load_dwordx4 v[240:243], v245, s[98:99]
	global_load_dwordx4 v[148:151], v245, s[98:99] offset:64
	s_add_u32 s98, s98, 0x80
	s_addc_u32 s99, s99, 0
	s_waitcnt vmcnt(10)
	s_waitcnt lgkmcnt(0)
	s_barrier
	s_setprio 1
	s_waitcnt lgkmcnt(0)
	v_mfma_f32_16x16x32_bf16 v[124:127], v[158:161], v[192:195], v[124:127]
	v_mfma_f32_16x16x32_bf16 v[120:123], v[166:169], v[192:195], v[120:123]
	v_mfma_f32_16x16x32_bf16 v[108:111], v[158:161], v[200:203], v[108:111]
	v_mfma_f32_16x16x32_bf16 v[104:107], v[166:169], v[200:203], v[104:107]
	v_mfma_f32_16x16x32_bf16 v[92:95], v[158:161], v[208:211], v[92:95]
	v_mfma_f32_16x16x32_bf16 v[88:91], v[166:169], v[208:211], v[88:91]
	v_mfma_f32_16x16x32_bf16 v[76:79], v[158:161], v[216:219], v[76:79]
	v_mfma_f32_16x16x32_bf16 v[72:75], v[166:169], v[216:219], v[72:75]
	v_mfma_f32_16x16x32_bf16 v[124:127], v[162:165], v[196:199], v[124:127]
	v_mfma_f32_16x16x32_bf16 v[120:123], v[170:173], v[196:199], v[120:123]
	v_mfma_f32_16x16x32_bf16 v[108:111], v[162:165], v[204:207], v[108:111]
	v_mfma_f32_16x16x32_bf16 v[104:107], v[170:173], v[204:207], v[104:107]
	v_mfma_f32_16x16x32_bf16 v[92:95], v[162:165], v[212:215], v[92:95]
	v_mfma_f32_16x16x32_bf16 v[88:91], v[170:173], v[212:215], v[88:91]
	v_mfma_f32_16x16x32_bf16 v[76:79], v[162:165], v[220:223], v[76:79]
	v_mfma_f32_16x16x32_bf16 v[72:75], v[170:173], v[220:223], v[72:75]
	s_setprio 0
	s_setprio 1
	v_mfma_f32_16x16x32_bf16 v[116:119], v[174:177], v[192:195], v[116:119]
	v_mfma_f32_16x16x32_bf16 v[112:115], v[184:187], v[192:195], v[112:115]
	v_mfma_f32_16x16x32_bf16 v[100:103], v[174:177], v[200:203], v[100:103]
	v_mfma_f32_16x16x32_bf16 v[96:99], v[184:187], v[200:203], v[96:99]
	v_mfma_f32_16x16x32_bf16 v[84:87], v[174:177], v[208:211], v[84:87]
	v_mfma_f32_16x16x32_bf16 v[80:83], v[184:187], v[208:211], v[80:83]
	v_mfma_f32_16x16x32_bf16 v[68:71], v[174:177], v[216:219], v[68:71]
	v_mfma_f32_16x16x32_bf16 v[64:67], v[184:187], v[216:219], v[64:67]
	v_mfma_f32_16x16x32_bf16 v[116:119], v[178:181], v[196:199], v[116:119]
	v_mfma_f32_16x16x32_bf16 v[112:115], v[188:191], v[196:199], v[112:115]
	v_mfma_f32_16x16x32_bf16 v[100:103], v[178:181], v[204:207], v[100:103]
	v_mfma_f32_16x16x32_bf16 v[96:99], v[188:191], v[204:207], v[96:99]
	v_mfma_f32_16x16x32_bf16 v[84:87], v[178:181], v[212:215], v[84:87]
	v_mfma_f32_16x16x32_bf16 v[80:83], v[188:191], v[212:215], v[80:83]
	v_mfma_f32_16x16x32_bf16 v[68:71], v[178:181], v[220:223], v[68:71]
	v_mfma_f32_16x16x32_bf16 v[64:67], v[188:191], v[220:223], v[64:67]
	s_cmp_lt_u32 s85, 2
	s_cbranch_scc1 .Ldtf_mal
	s_cmp_eq_u32 s85, 2
	s_cbranch_scc1 .Ldtf_ma2
	v_mfma_f32_16x16x32_bf16 v[246:249], v[232:235], v[216:219], v[246:249]
	v_mfma_f32_16x16x32_bf16 v[246:249], v[236:239], v[220:223], v[246:249]
	s_branch .Ldtf_max
.Ldtf_ma2:
	v_mfma_f32_16x16x32_bf16 v[246:249], v[232:235], v[208:211], v[246:249]
	v_mfma_f32_16x16x32_bf16 v[246:249], v[236:239], v[212:215], v[246:249]
	s_branch .Ldtf_max
.Ldtf_mal:
	s_cmp_eq_u32 s85, 0
	s_cbranch_scc1 .Ldtf_ma0
	v_mfma_f32_16x16x32_bf16 v[246:249], v[232:235], v[200:203], v[246:249]
	v_mfma_f32_16x16x32_bf16 v[246:249], v[236:239], v[204:207], v[246:249]
	s_branch .Ldtf_max
.Ldtf_ma0:
	v_mfma_f32_16x16x32_bf16 v[246:249], v[232:235], v[192:195], v[246:249]
	v_mfma_f32_16x16x32_bf16 v[246:249], v[236:239], v[196:199], v[246:249]
.Ldtf_max:
	s_setprio 0
	s_barrier
	s_add_i32 s56, s50, s39
	v_lshl_add_u64 v[152:153], s[34:35], 0, v[130:131]
	s_mov_b32 m0, s56
	ds_read_b128 v[192:195], v156 offset:16384
	ds_read_b128 v[196:199], v156 offset:17408
	ds_read_b128 v[200:203], v156 offset:18432
	ds_read_b128 v[204:207], v156 offset:19456
	ds_read_b128 v[208:211], v156 offset:20480
	ds_read_b128 v[212:215], v156 offset:21504
	ds_read_b128 v[216:219], v156 offset:22528
	ds_read_b128 v[220:223], v156 offset:23552
	global_load_lds_dwordx4 v[152:153], off
	s_add_i32 m0, s56, 0x2000
	s_add_u32 s56, s34, 0x40000
	v_lshl_add_u64 v[224:225], s[34:35], 0, v[134:135]
	s_addc_u32 s57, s35, 0
	s_add_i32 s58, s51, s39
	global_load_lds_dwordx4 v[224:225], off
	v_lshl_add_u64 v[226:227], s[56:57], 0, v[130:131]
	s_mov_b32 m0, s58
	v_lshl_add_u64 v[228:229], s[36:37], 0, v[132:133]
	global_load_lds_dwordx4 v[226:227], off
	v_lshl_add_u64 v[226:227], s[56:57], 0, v[134:135]
	s_add_i32 m0, s58, 0x2000
	s_nop 0
	global_load_lds_dwordx4 v[226:227], off
	v_lshl_add_u64 v[226:227], s[36:37], 0, v[128:129]
	s_mov_b32 m0, s7
	s_nop 0
	global_load_lds_dwordx4 v[226:227], off
	s_mov_b32 m0, s40
	s_nop 0
	global_load_lds_dwordx4 v[228:229], off
	s_waitcnt vmcnt(10)
	s_waitcnt lgkmcnt(0)
	s_barrier
	s_setprio 1
	s_waitcnt lgkmcnt(0)
	v_mfma_f32_16x16x32_bf16 v[60:63], v[158:161], v[192:195], v[60:63]
	v_mfma_f32_16x16x32_bf16 v[56:59], v[166:169], v[192:195], v[56:59]
	v_mfma_f32_16x16x32_bf16 v[44:47], v[158:161], v[200:203], v[44:47]
	v_mfma_f32_16x16x32_bf16 v[40:43], v[166:169], v[200:203], v[40:43]
	v_mfma_f32_16x16x32_bf16 v[28:31], v[158:161], v[208:211], v[28:31]
	v_mfma_f32_16x16x32_bf16 v[24:27], v[166:169], v[208:211], v[24:27]
	v_mfma_f32_16x16x32_bf16 v[12:15], v[158:161], v[216:219], v[12:15]
	v_mfma_f32_16x16x32_bf16 v[8:11], v[166:169], v[216:219], v[8:11]
	v_mfma_f32_16x16x32_bf16 v[60:63], v[162:165], v[196:199], v[60:63]
	v_mfma_f32_16x16x32_bf16 v[56:59], v[170:173], v[196:199], v[56:59]
	v_mfma_f32_16x16x32_bf16 v[44:47], v[162:165], v[204:207], v[44:47]
	v_mfma_f32_16x16x32_bf16 v[40:43], v[170:173], v[204:207], v[40:43]
	v_mfma_f32_16x16x32_bf16 v[28:31], v[162:165], v[212:215], v[28:31]
	v_mfma_f32_16x16x32_bf16 v[24:27], v[170:173], v[212:215], v[24:27]
	v_mfma_f32_16x16x32_bf16 v[12:15], v[162:165], v[220:223], v[12:15]
	v_mfma_f32_16x16x32_bf16 v[8:11], v[170:173], v[220:223], v[8:11]
	s_setprio 0
	s_setprio 1
	v_mfma_f32_16x16x32_bf16 v[52:55], v[174:177], v[192:195], v[52:55]
	v_mfma_f32_16x16x32_bf16 v[48:51], v[184:187], v[192:195], v[48:51]
	v_mfma_f32_16x16x32_bf16 v[36:39], v[174:177], v[200:203], v[36:39]
	v_mfma_f32_16x16x32_bf16 v[32:35], v[184:187], v[200:203], v[32:35]
	v_mfma_f32_16x16x32_bf16 v[20:23], v[174:177], v[208:211], v[20:23]
	v_mfma_f32_16x16x32_bf16 v[16:19], v[184:187], v[208:211], v[16:19]
	v_mfma_f32_16x16x32_bf16 v[4:7], v[174:177], v[216:219], v[4:7]
	v_mfma_f32_16x16x32_bf16 v[0:3], v[184:187], v[216:219], v[0:3]
	v_mfma_f32_16x16x32_bf16 v[52:55], v[178:181], v[196:199], v[52:55]
	v_mfma_f32_16x16x32_bf16 v[48:51], v[188:191], v[196:199], v[48:51]
	v_mfma_f32_16x16x32_bf16 v[36:39], v[178:181], v[204:207], v[36:39]
	v_mfma_f32_16x16x32_bf16 v[32:35], v[188:191], v[204:207], v[32:35]
	v_mfma_f32_16x16x32_bf16 v[20:23], v[178:181], v[212:215], v[20:23]
	v_mfma_f32_16x16x32_bf16 v[16:19], v[188:191], v[212:215], v[16:19]
	v_mfma_f32_16x16x32_bf16 v[4:7], v[178:181], v[220:223], v[4:7]
	v_mfma_f32_16x16x32_bf16 v[0:3], v[188:191], v[220:223], v[0:3]
	s_cmp_lt_u32 s85, 2
	s_cbranch_scc1 .Ldtf_mbl
	s_cmp_eq_u32 s85, 2
	s_cbranch_scc1 .Ldtf_mb2
	v_mfma_f32_16x16x32_bf16 v[250:253], v[232:235], v[216:219], v[250:253]
	v_mfma_f32_16x16x32_bf16 v[250:253], v[236:239], v[220:223], v[250:253]
	s_branch .Ldtf_mbx
.Ldtf_mb2:
	v_mfma_f32_16x16x32_bf16 v[250:253], v[232:235], v[208:211], v[250:253]
	v_mfma_f32_16x16x32_bf16 v[250:253], v[236:239], v[212:215], v[250:253]
	s_branch .Ldtf_mbx
.Ldtf_mbl:
	s_cmp_eq_u32 s85, 0
	s_cbranch_scc1 .Ldtf_mb0
	v_mfma_f32_16x16x32_bf16 v[250:253], v[232:235], v[200:203], v[250:253]
	v_mfma_f32_16x16x32_bf16 v[250:253], v[236:239], v[204:207], v[250:253]
	s_branch .Ldtf_mbx
.Ldtf_mb0:
	v_mfma_f32_16x16x32_bf16 v[250:253], v[232:235], v[192:195], v[250:253]
	v_mfma_f32_16x16x32_bf16 v[250:253], v[236:239], v[196:199], v[250:253]
.Ldtf_mbx:
	s_setprio 0
	s_barrier
	s_add_i32 s56, 0, 0x18000
	v_add_u32_e32 v136, s56, v145
	s_add_i32 s57, 0, 0x1c000
	ds_read_b128 v[158:161], v136
	ds_read_b128 v[162:165], v136 offset:1024
	ds_read_b128 v[166:169], v136 offset:2048
	ds_read_b128 v[170:173], v136 offset:3072
	v_add_u32_e32 v136, s57, v145
	ds_read_b128 v[174:177], v136
	ds_read_b128 v[178:181], v136 offset:1024
	ds_read_b128 v[184:187], v136 offset:2048
	ds_read_b128 v[188:191], v136 offset:3072
	s_add_u32 s36, s36, 0x40000
	s_addc_u32 s37, s37, 0
	s_mov_b32 m0, s41
	v_lshl_add_u64 v[230:231], s[36:37], 0, v[128:129]
	ds_read_b128 v[192:195], v156 offset:32768
	ds_read_b128 v[196:199], v156 offset:33792
	ds_read_b128 v[200:203], v156 offset:34816
	ds_read_b128 v[204:207], v156 offset:35840
	ds_read_b128 v[208:211], v156 offset:36864
	ds_read_b128 v[212:215], v156 offset:37888
	ds_read_b128 v[216:219], v156 offset:38912
	ds_read_b128 v[220:223], v156 offset:39936
	global_load_lds_dwordx4 v[230:231], off
	v_lshl_add_u64 v[230:231], s[36:37], 0, v[132:133]
	s_mov_b32 m0, s42
	s_nop 0
	global_load_lds_dwordx4 v[230:231], off
	global_load_dwordx4 v[232:235], v245, s[98:99]
	global_load_dwordx4 v[236:239], v245, s[98:99] offset:64
	s_add_u32 s98, s98, 0x80
	s_addc_u32 s99, s99, 0
	s_waitcnt vmcnt(10)
	s_waitcnt lgkmcnt(0)
	s_barrier
	s_setprio 1
	s_waitcnt lgkmcnt(0)
	v_mfma_f32_16x16x32_bf16 v[124:127], v[158:161], v[192:195], v[124:127]
	v_mfma_f32_16x16x32_bf16 v[120:123], v[166:169], v[192:195], v[120:123]
	v_mfma_f32_16x16x32_bf16 v[108:111], v[158:161], v[200:203], v[108:111]
	v_mfma_f32_16x16x32_bf16 v[104:107], v[166:169], v[200:203], v[104:107]
	v_mfma_f32_16x16x32_bf16 v[92:95], v[158:161], v[208:211], v[92:95]
	v_mfma_f32_16x16x32_bf16 v[88:91], v[166:169], v[208:211], v[88:91]
	v_mfma_f32_16x16x32_bf16 v[76:79], v[158:161], v[216:219], v[76:79]
	v_mfma_f32_16x16x32_bf16 v[72:75], v[166:169], v[216:219], v[72:75]
	v_mfma_f32_16x16x32_bf16 v[124:127], v[162:165], v[196:199], v[124:127]
	v_mfma_f32_16x16x32_bf16 v[120:123], v[170:173], v[196:199], v[120:123]
	v_mfma_f32_16x16x32_bf16 v[108:111], v[162:165], v[204:207], v[108:111]
	v_mfma_f32_16x16x32_bf16 v[104:107], v[170:173], v[204:207], v[104:107]
	v_mfma_f32_16x16x32_bf16 v[92:95], v[162:165], v[212:215], v[92:95]
	v_mfma_f32_16x16x32_bf16 v[88:91], v[170:173], v[212:215], v[88:91]
	v_mfma_f32_16x16x32_bf16 v[76:79], v[162:165], v[220:223], v[76:79]
	v_mfma_f32_16x16x32_bf16 v[72:75], v[170:173], v[220:223], v[72:75]
	s_setprio 0
	s_setprio 1
	v_mfma_f32_16x16x32_bf16 v[116:119], v[174:177], v[192:195], v[116:119]
	v_mfma_f32_16x16x32_bf16 v[112:115], v[184:187], v[192:195], v[112:115]
	v_mfma_f32_16x16x32_bf16 v[100:103], v[174:177], v[200:203], v[100:103]
	v_mfma_f32_16x16x32_bf16 v[96:99], v[184:187], v[200:203], v[96:99]
	v_mfma_f32_16x16x32_bf16 v[84:87], v[174:177], v[208:211], v[84:87]
	v_mfma_f32_16x16x32_bf16 v[80:83], v[184:187], v[208:211], v[80:83]
	v_mfma_f32_16x16x32_bf16 v[68:71], v[174:177], v[216:219], v[68:71]
	v_mfma_f32_16x16x32_bf16 v[64:67], v[184:187], v[216:219], v[64:67]
	v_mfma_f32_16x16x32_bf16 v[116:119], v[178:181], v[196:199], v[116:119]
	v_mfma_f32_16x16x32_bf16 v[112:115], v[188:191], v[196:199], v[112:115]
	v_mfma_f32_16x16x32_bf16 v[100:103], v[178:181], v[204:207], v[100:103]
	v_mfma_f32_16x16x32_bf16 v[96:99], v[188:191], v[204:207], v[96:99]
	v_mfma_f32_16x16x32_bf16 v[84:87], v[178:181], v[212:215], v[84:87]
	v_mfma_f32_16x16x32_bf16 v[80:83], v[188:191], v[212:215], v[80:83]
	v_mfma_f32_16x16x32_bf16 v[68:71], v[178:181], v[220:223], v[68:71]
	v_mfma_f32_16x16x32_bf16 v[64:67], v[188:191], v[220:223], v[64:67]
	s_cmp_lt_u32 s85, 2
	s_cbranch_scc1 .Ldtf_mcl
	s_cmp_eq_u32 s85, 2
	s_cbranch_scc1 .Ldtf_mc2
	v_mfma_f32_16x16x32_bf16 v[246:249], v[240:243], v[216:219], v[246:249]
	v_mfma_f32_16x16x32_bf16 v[246:249], v[148:151], v[220:223], v[246:249]
	s_branch .Ldtf_mcx
.Ldtf_mc2:
	v_mfma_f32_16x16x32_bf16 v[246:249], v[240:243], v[208:211], v[246:249]
	v_mfma_f32_16x16x32_bf16 v[246:249], v[148:151], v[212:215], v[246:249]
	s_branch .Ldtf_mcx
.Ldtf_mcl:
	s_cmp_eq_u32 s85, 0
	s_cbranch_scc1 .Ldtf_mc0
	v_mfma_f32_16x16x32_bf16 v[246:249], v[240:243], v[200:203], v[246:249]
	v_mfma_f32_16x16x32_bf16 v[246:249], v[148:151], v[204:207], v[246:249]
	s_branch .Ldtf_mcx
.Ldtf_mc0:
	v_mfma_f32_16x16x32_bf16 v[246:249], v[240:243], v[192:195], v[246:249]
	v_mfma_f32_16x16x32_bf16 v[246:249], v[148:151], v[196:199], v[246:249]
.Ldtf_mcx:
	s_setprio 0
	s_barrier
	s_add_i32 s36, s56, s39
	v_lshl_add_u64 v[152:153], v[152:153], 0, s[12:13]
	s_mov_b32 m0, s36
	ds_read_b128 v[192:195], v156 offset:49152
	ds_read_b128 v[196:199], v156 offset:50176
	ds_read_b128 v[200:203], v156 offset:51200
	ds_read_b128 v[204:207], v156 offset:52224
	ds_read_b128 v[208:211], v156 offset:53248
	ds_read_b128 v[212:215], v156 offset:54272
	ds_read_b128 v[216:219], v156 offset:55296
	ds_read_b128 v[220:223], v156 offset:56320
	global_load_lds_dwordx4 v[152:153], off
	s_add_i32 m0, s36, 0x2000
	s_add_u32 s34, s34, 0x40080
	v_lshl_add_u64 v[152:153], v[224:225], 0, s[12:13]
	s_addc_u32 s35, s35, 0
	s_add_i32 s36, s57, s39
	global_load_lds_dwordx4 v[152:153], off
	v_lshl_add_u64 v[152:153], s[34:35], 0, v[130:131]
	s_mov_b32 m0, s36
	s_nop 0
	global_load_lds_dwordx4 v[152:153], off
	v_lshl_add_u64 v[152:153], s[34:35], 0, v[134:135]
	s_add_i32 m0, s36, 0x2000
	s_nop 0
	global_load_lds_dwordx4 v[152:153], off
	v_lshl_add_u64 v[152:153], v[226:227], 0, s[12:13]
	s_mov_b32 m0, s45
	s_nop 0
	global_load_lds_dwordx4 v[152:153], off
	v_lshl_add_u64 v[152:153], v[228:229], 0, s[12:13]
	s_mov_b32 m0, s46
	s_nop 0
	global_load_lds_dwordx4 v[152:153], off
	s_waitcnt vmcnt(10)
	s_waitcnt lgkmcnt(0)
	s_barrier
	s_setprio 1
	s_waitcnt lgkmcnt(0)
	v_mfma_f32_16x16x32_bf16 v[60:63], v[158:161], v[192:195], v[60:63]
	v_mfma_f32_16x16x32_bf16 v[56:59], v[166:169], v[192:195], v[56:59]
	v_mfma_f32_16x16x32_bf16 v[44:47], v[158:161], v[200:203], v[44:47]
	v_mfma_f32_16x16x32_bf16 v[40:43], v[166:169], v[200:203], v[40:43]
	v_mfma_f32_16x16x32_bf16 v[28:31], v[158:161], v[208:211], v[28:31]
	v_mfma_f32_16x16x32_bf16 v[24:27], v[166:169], v[208:211], v[24:27]
	v_mfma_f32_16x16x32_bf16 v[12:15], v[158:161], v[216:219], v[12:15]
	v_mfma_f32_16x16x32_bf16 v[8:11], v[166:169], v[216:219], v[8:11]
	v_mfma_f32_16x16x32_bf16 v[60:63], v[162:165], v[196:199], v[60:63]
	v_mfma_f32_16x16x32_bf16 v[56:59], v[170:173], v[196:199], v[56:59]
	v_mfma_f32_16x16x32_bf16 v[44:47], v[162:165], v[204:207], v[44:47]
	v_mfma_f32_16x16x32_bf16 v[40:43], v[170:173], v[204:207], v[40:43]
	v_mfma_f32_16x16x32_bf16 v[28:31], v[162:165], v[212:215], v[28:31]
	v_mfma_f32_16x16x32_bf16 v[24:27], v[170:173], v[212:215], v[24:27]
	v_mfma_f32_16x16x32_bf16 v[12:15], v[162:165], v[220:223], v[12:15]
	v_mfma_f32_16x16x32_bf16 v[8:11], v[170:173], v[220:223], v[8:11]
	s_setprio 0
	s_setprio 1
	v_mfma_f32_16x16x32_bf16 v[52:55], v[174:177], v[192:195], v[52:55]
	v_mfma_f32_16x16x32_bf16 v[48:51], v[184:187], v[192:195], v[48:51]
	v_mfma_f32_16x16x32_bf16 v[36:39], v[174:177], v[200:203], v[36:39]
	v_mfma_f32_16x16x32_bf16 v[32:35], v[184:187], v[200:203], v[32:35]
	v_mfma_f32_16x16x32_bf16 v[20:23], v[174:177], v[208:211], v[20:23]
	v_mfma_f32_16x16x32_bf16 v[16:19], v[184:187], v[208:211], v[16:19]
	v_mfma_f32_16x16x32_bf16 v[4:7], v[174:177], v[216:219], v[4:7]
	v_mfma_f32_16x16x32_bf16 v[0:3], v[184:187], v[216:219], v[0:3]
	v_mfma_f32_16x16x32_bf16 v[52:55], v[178:181], v[196:199], v[52:55]
	v_mfma_f32_16x16x32_bf16 v[48:51], v[188:191], v[196:199], v[48:51]
	v_mfma_f32_16x16x32_bf16 v[36:39], v[178:181], v[204:207], v[36:39]
	v_mfma_f32_16x16x32_bf16 v[32:35], v[188:191], v[204:207], v[32:35]
	v_mfma_f32_16x16x32_bf16 v[20:23], v[178:181], v[212:215], v[20:23]
	v_mfma_f32_16x16x32_bf16 v[16:19], v[188:191], v[212:215], v[16:19]
	v_mfma_f32_16x16x32_bf16 v[4:7], v[178:181], v[220:223], v[4:7]
	v_mfma_f32_16x16x32_bf16 v[0:3], v[188:191], v[220:223], v[0:3]
	s_cmp_lt_u32 s85, 2
	s_cbranch_scc1 .Ldtf_mdl
	s_cmp_eq_u32 s85, 2
	s_cbranch_scc1 .Ldtf_md2
	v_mfma_f32_16x16x32_bf16 v[250:253], v[240:243], v[216:219], v[250:253]
	v_mfma_f32_16x16x32_bf16 v[250:253], v[148:151], v[220:223], v[250:253]
	s_branch .Ldtf_mdx
.Ldtf_md2:
	v_mfma_f32_16x16x32_bf16 v[250:253], v[240:243], v[208:211], v[250:253]
	v_mfma_f32_16x16x32_bf16 v[250:253], v[148:151], v[212:215], v[250:253]
	s_branch .Ldtf_mdx
.Ldtf_mdl:
	s_cmp_eq_u32 s85, 0
	s_cbranch_scc1 .Ldtf_md0
	v_mfma_f32_16x16x32_bf16 v[250:253], v[240:243], v[200:203], v[250:253]
	v_mfma_f32_16x16x32_bf16 v[250:253], v[148:151], v[204:207], v[250:253]
	s_branch .Ldtf_mdx
.Ldtf_md0:
	v_mfma_f32_16x16x32_bf16 v[250:253], v[240:243], v[192:195], v[250:253]
	v_mfma_f32_16x16x32_bf16 v[250:253], v[148:151], v[196:199], v[250:253]
.Ldtf_mdx:
	s_setprio 0
	s_barrier
	s_add_i32 s55, s55, 2
	s_add_u32 s30, s30, 0x100
	s_addc_u32 s31, s31, 0
	s_add_u32 s53, s53, 0x100
	s_addc_u32 s54, s54, 0
	s_cmp_gt_u32 s55, 13
	s_cbranch_scc0 .Ldtf_loop
.Ldtf_exit:
	s_and_b64 vcc, exec, s[14:15]
	s_cbranch_vccz .LBB0_401
	s_barrier
.LBB0_401:
	s_cmp_lg_u32 s84, 0
	s_cbranch_scc0 .Ldtf_noepi
	v_and_b32_e32 v254, 15, v182
	v_bfe_u32 v255, v182, 6, 2
	v_lshl_or_b32 v254, v255, 4, v254
	v_bfe_u32 v255, v182, 8, 1
	v_lshl_or_b32 v254, v255, 6, v254
	v_lshl_add_u32 v254, s4, 8, v254
	v_lshlrev_b32_e32 v254, 6, v254
	v_bfe_u32 v255, v182, 4, 2
	v_lshl_add_u32 v254, v255, 4, v254
	v_add_u32_e32 v255, 0x2000, v254
	global_store_dwordx4 v254, v[246:249], s[100:101]
	global_store_dwordx4 v255, v[250:253], s[100:101]
	v_mov_b64_e32 v[148:149], 0x900
	v_mov_b64_e32 v[150:151], 0x8ff
	s_mov_b32 s84, 0

.LBB0_1947:
	v_readlane_b32 s4, v244, 47
	s_cmp_lt_i32 s4, 10
	s_cselect_b64 s[2:3], -1, 0
	s_and_b64 s[2:3], s[2:3], s[0:1]
	s_cmpk_lt_i32 s69, 0x600
	s_cselect_b64 s[0:1], -1, 0
	s_and_b64 s[0:1], s[2:3], s[0:1]
	s_andn2_b64 vcc, exec, s[0:1]
	v_readlane_b32 s5, v244, 48
	v_readlane_b32 s6, v244, 49
	v_readlane_b32 s7, v244, 50
	s_cbranch_vccnz .LBB0_1956
	v_and_b32_e32 v249, 63, v182
	v_readlane_b32 s4, v244, 6
	v_readlane_b32 s5, v244, 7
	v_readlane_b32 s6, v244, 39
	v_readlane_b32 s7, v244, 40
	v_readlane_b32 s8, v244, 41
	v_readlane_b32 s9, v244, 42
	v_lshlrev_b32_e32 v242, 2, v249
	s_nop 3
	global_load_dword v216, v242, s[6:7] offset:0
	global_load_dword v217, v242, s[6:7] offset:256
	global_load_dword v218, v242, s[6:7] offset:512
	global_load_dword v219, v242, s[6:7] offset:768
	global_load_dword v220, v242, s[8:9] offset:0
	global_load_dword v221, v242, s[8:9] offset:256
	global_load_dword v222, v242, s[8:9] offset:512
	global_load_dword v223, v242, s[8:9] offset:768
	v_and_b32_e32 v243, 15, v182
	v_bfe_u32 v245, v182, 4, 2
	v_lshl_or_b32 v246, s88, 4, v243
	v_lshlrev_b32_e32 v228, 11, v246
	v_lshl_add_u32 v238, v245, 3, v228
	v_lshl_add_u32 v228, v245, 4, v228
	v_add_u32_e32 v229, 0x40000, v228
	v_add_u32_e32 v239, 0x40000, v238
	v_lshlrev_b32_e32 v230, 4, v246
	v_mul_u32_u24_e32 v231, 528, v243
	v_lshl_add_u32 v232, v245, 3, v231
	v_mul_u32_u24_e32 v231, 528, v243
	v_lshl_add_u32 v231, v245, 4, v231
	v_lshrrev_b32_e32 v243, 5, v182
	v_and_b32_e32 v245, 31, v182
	v_lshlrev_b32_e32 v245, 4, v245
	v_lshl_add_u32 v224, v243, 11, v245
	v_mul_u32_u24_e32 v225, 5120, v243
	v_add_u32_e32 v225, v225, v245
	v_mul_u32_u24_e32 v226, 528, v243
	v_add_u32_e32 v226, v226, v245
	v_add_u32_e32 v227, 67584, v226
	v_and_b32_e32 v250, 3, v243
	v_bfe_u32 v242, v243, 2, 1
	v_lshl_or_b32 v250, v242, 4, v250
	v_bfe_u32 v242, v243, 3, 1
	v_lshl_or_b32 v250, v242, 2, v250
	v_mul_u32_u24_e32 v250, 528, v250
	v_add_u32_e32 v250, v250, v245
	v_add_u32_e32 v251, 67584, v250
	v_xor_b32_e32 v236, 16, v249
	v_lshlrev_b32_e32 v236, 2, v236
	v_xor_b32_e32 v237, 32, v249
	v_lshlrev_b32_e32 v237, 2, v237
	v_mov_b32_e32 v181, 0x358637bd
	s_waitcnt vmcnt(0)
	v_mul_f32_e32 v216, v216, v220
	v_mul_f32_e32 v217, v217, v221
	v_mul_f32_e32 v218, v218, v222
	v_mul_f32_e32 v219, v219, v223
	v_max_f32_e64 v216, |v216|, |v217|
	v_max_f32_e64 v218, |v218|, |v219|
	v_max_f32_e32 v216, v216, v218
	v_xor_b32_e32 v242, 1, v249
	v_lshlrev_b32_e32 v242, 2, v242
	ds_bpermute_b32 v243, v242, v216
	s_waitcnt lgkmcnt(0)
	v_max_f32_e32 v216, v216, v243
	v_xor_b32_e32 v242, 2, v249
	v_lshlrev_b32_e32 v242, 2, v242
	ds_bpermute_b32 v243, v242, v216
	s_waitcnt lgkmcnt(0)
	v_max_f32_e32 v216, v216, v243
	v_xor_b32_e32 v242, 4, v249
	v_lshlrev_b32_e32 v242, 2, v242
	ds_bpermute_b32 v243, v242, v216
	s_waitcnt lgkmcnt(0)
	v_max_f32_e32 v216, v216, v243
	v_xor_b32_e32 v242, 8, v249
	v_lshlrev_b32_e32 v242, 2, v242
	ds_bpermute_b32 v243, v242, v216
	s_waitcnt lgkmcnt(0)
	v_max_f32_e32 v216, v216, v243
	v_xor_b32_e32 v242, 16, v249
	v_lshlrev_b32_e32 v242, 2, v242
	ds_bpermute_b32 v243, v242, v216
	s_waitcnt lgkmcnt(0)
	v_max_f32_e32 v216, v216, v243
	v_xor_b32_e32 v242, 32, v249
	v_lshlrev_b32_e32 v242, 2, v242
	ds_bpermute_b32 v243, v242, v216
	s_waitcnt lgkmcnt(0)
	v_max_f32_e32 v216, v216, v243
	v_mul_f32_e32 v180, 0x41b8aa3b, v216
	s_and_b32 s0, s69, 31
	s_lshr_b32 s1, s69, 8
	s_lshl_b32 s1, s1, 5
	s_add_i32 s1, s1, s0
	s_mul_i32 s0, s1, 2731
	s_lshr_b32 s0, s0, 16
	s_mul_i32 s17, s0, 24
	s_sub_i32 s1, s1, s17
	s_bfe_u32 s17, s69, 0x30005
	s_mul_i32 s17, s17, 24
	s_add_i32 s1, s1, s17
	s_lshl_b32 s11, s1, 19
	s_lshl_b32 s12, s0, 9
	s_add_u32 s11, s11, s12
	s_add_u32 s12, s11, 0xf000000
	s_add_u32 s10, s4, s12
	s_addc_u32 s11, s5, 0
	s_lshl_b32 s12, s1, 12
	s_lshl_b32 s13, s0, 2
	s_add_u32 s12, s12, s13
	s_add_u32 s12, s12, 0x1fa60000
	s_add_u32 s12, s4, s12
	s_addc_u32 s13, s5, 0
	global_load_dwordx4 v[0:3], v228, s[10:11] offset:0
	global_load_dwordx4 v[4:7], v228, s[10:11] offset:64
	global_load_dwordx4 v[8:11], v228, s[10:11] offset:128
	global_load_dwordx4 v[12:15], v228, s[10:11] offset:192
	global_load_dwordx4 v[16:19], v228, s[10:11] offset:256
	global_load_dwordx4 v[20:23], v228, s[10:11] offset:320
	global_load_dwordx4 v[24:27], v228, s[10:11] offset:384
	global_load_dwordx4 v[28:31], v228, s[10:11] offset:448
	global_load_dwordx4 v[32:35], v229, s[10:11] offset:0
	global_load_dwordx4 v[36:39], v229, s[10:11] offset:64
	global_load_dwordx4 v[40:43], v229, s[10:11] offset:128
	global_load_dwordx4 v[44:47], v229, s[10:11] offset:192
	global_load_dwordx4 v[48:51], v229, s[10:11] offset:256
	global_load_dwordx4 v[52:55], v229, s[10:11] offset:320
	global_load_dwordx4 v[56:59], v229, s[10:11] offset:384
	global_load_dwordx4 v[60:63], v229, s[10:11] offset:448
	global_load_dword v247, v230, s[12:13]
	global_load_dword v248, v230, s[12:13] offset:2048
	s_lshr_b32 s10, s1, 5
	s_sub_i32 s11, s1, 64
	s_lshr_b32 s11, s11, 4
	s_add_i32 s11, s11, 2
	s_cmp_lt_u32 s1, 64
	s_cselect_b32 s10, s10, s11
	s_lshl_b32 s11, s10, 19
	s_lshl_b32 s12, s0, 9
	s_add_u32 s11, s11, s12
	s_add_u32 s11, s11, 0x15040000
	s_add_u32 s6, s4, s11
	s_addc_u32 s7, s5, 0
	global_load_dwordx4 v[184:187], v224, s[6:7]
	s_add_u32 s6, s6, 0x8000
	s_addc_u32 s7, s7, 0
	global_load_dwordx4 v[188:191], v224, s[6:7]
	s_add_u32 s6, s6, 0x8000
	s_addc_u32 s7, s7, 0
	global_load_dwordx4 v[192:195], v224, s[6:7]
	s_add_u32 s6, s6, 0x8000
	s_addc_u32 s7, s7, 0
	global_load_dwordx4 v[196:199], v224, s[6:7]
	s_add_u32 s6, s6, 0x8000
	s_addc_u32 s7, s7, 0
	global_load_dwordx4 v[200:203], v224, s[6:7]
	s_add_u32 s6, s6, 0x8000
	s_addc_u32 s7, s7, 0
	global_load_dwordx4 v[204:207], v224, s[6:7]
	s_add_u32 s6, s6, 0x8000
	s_addc_u32 s7, s7, 0
	global_load_dwordx4 v[208:211], v224, s[6:7]
	s_add_u32 s6, s6, 0x8000
	s_addc_u32 s7, s7, 0
	global_load_dwordx4 v[212:215], v224, s[6:7]
